# top-k: dropped per-block pad nops in the counting probes; row maximum reduced with DPP instead of six bpermute round trips
# baseline (speedup 1.0000x reference)
; __device__ __forceinline__ void b1_phase(const bf16* QI, const bf16* KI, const float* WI, float* SCRb  , unsigned long long* MASK,
;                                          LAS unsigned char* lds, int vcu, int G, int tid) {
;     ...
;                 unsigned kmax = 0u;
; #pragma unroll
;                 for (int j = 0; j < 64; ++j) kmax = uu[j] > kmax ? uu[j] : kmax;
; #pragma unroll
;                 for (int o = 1; o < 64; o <<= 1) { const unsigned t_ = (unsigned)__shfl_xor((int)kmax, o); kmax = t_ > kmax ? t_ : kmax; }
;                 kmax = (unsigned)__builtin_amdgcn_readfirstlane((int)kmax);
;                 unsigned a = 1u, b = kmax + 1u; if (b == 0u) b = 0xFFFFFFFFu;
;                 float fa = (float)(limit - 256) + 0.5f, fb = -255.5f; int side = 0;
;                 bool done = false;
;                 if (b > 0x80000001u) {
;                     unsigned l0 = 0u, l1 = 0u, l2 = 0u, l3 = 0u; const unsigned csign = 0x80000000u;
; #pragma unroll
;                     for (int j = 0; j < 64; j += 4) cnt_lt4(l0, l1, l2, l3, uu[j], uu[j + 1], uu[j + 2], uu[j + 3], csign);
.Ltk_tf_done:
.LBB0_661:
	s_waitcnt vmcnt(0)
	v_add_f32_e32 v2, 0, v66
	v_cmp_lt_i32_e32 vcc, -1, v2
	v_readlane_b32 s0, v251, 12
	v_mov_b32_e32 v66, 1
	v_cndmask_b32_e32 v3, -1, v239, vcc
	v_xor_b32_e32 v67, v3, v2
	s_and_b64 vcc, exec, s[6:7]
	v_readlane_b32 s1, v251, 13
	s_cbranch_vccz .LBB0_666
	v_max_u32_e32 v2, v6, v67
	v_max3_u32 v2, v8, v0, v2
	v_max3_u32 v2, v10, v4, v2
	v_max3_u32 v2, v12, v5, v2
	v_max3_u32 v2, v14, v7, v2
	v_max3_u32 v2, v15, v9, v2
	v_max3_u32 v2, v17, v11, v2
	v_max3_u32 v2, v18, v13, v2
	v_max3_u32 v2, v20, v16, v2
	v_max3_u32 v2, v22, v19, v2
	v_max3_u32 v2, v24, v21, v2
	v_max3_u32 v2, v26, v23, v2
	v_max3_u32 v2, v28, v25, v2
	v_max3_u32 v2, v30, v27, v2
	v_max3_u32 v2, v32, v29, v2
	v_max3_u32 v2, v34, v31, v2
	v_max3_u32 v2, v37, v33, v2
	v_max3_u32 v2, v39, v35, v2
	v_max3_u32 v2, v41, v36, v2
	v_max3_u32 v2, v43, v38, v2
	v_max3_u32 v2, v45, v40, v2
	v_max3_u32 v2, v47, v42, v2
	v_max3_u32 v2, v49, v44, v2
	v_max3_u32 v2, v51, v46, v2
	v_max3_u32 v2, v53, v48, v2
	v_max3_u32 v2, v55, v50, v2
	v_max3_u32 v2, v57, v52, v2
	v_max3_u32 v2, v59, v54, v2
	v_max3_u32 v2, v61, v56, v2
	v_max3_u32 v2, v63, v58, v2
	v_max3_u32 v2, v64, v60, v2
	v_max3_u32 v2, v65, v62, v2
	s_mov_b32 s4, 1
	s_nop 1
	v_max_u32_dpp v2, v2, v2 row_shr:1 row_mask:0xf bank_mask:0xf bound_ctrl:1
	s_nop 1
	v_max_u32_dpp v2, v2, v2 row_shr:2 row_mask:0xf bank_mask:0xf bound_ctrl:1
	s_nop 1
	v_max_u32_dpp v2, v2, v2 row_shr:4 row_mask:0xf bank_mask:0xf bound_ctrl:1
	s_nop 1
	v_max_u32_dpp v2, v2, v2 row_shr:8 row_mask:0xf bank_mask:0xf bound_ctrl:1
	s_nop 1
	v_max_u32_dpp v2, v2, v2 row_bcast:15 row_mask:0xa bank_mask:0xf
	s_nop 1
	v_max_u32_dpp v2, v2, v2 row_bcast:31 row_mask:0xc bank_mask:0xf
	s_nop 0
	v_readlane_b32 s0, v2, 63
	s_nop 1
	v_add_co_u32_e64 v3, s[0:1], s0, 1
	s_nop 1
	v_cndmask_b32_e64 v66, v3, -1, s[0:1]
	s_mov_b32 s0, 0x80000001
	v_cmp_lt_u32_e32 vcc, s0, v66
	s_cbranch_vccz .LBB0_668
	s_lshr_b32 s98, s99, 4
	s_lshl_b32 s98, s98, 4
	s_sub_u32 s98, 48, s98
	v_mov_b32_e32 v2, s98
	v_mov_b32_e32 v3, v1
	v_mov_b32_e32 v68, v1
	v_mov_b32_e32 v69, v1
	v_cmp_lt_u32_e64 s[0:1], v67, v239
	v_cmp_lt_u32_e64 s[2:3], v6, v239
	v_cmp_lt_u32_e64 s[4:5], v0, v239
	v_cmp_lt_u32_e64 s[6:7], v8, v239
	v_addc_co_u32_e64 v2, s[0:1], v2, 0, s[0:1]
	v_addc_co_u32_e64 v3, s[2:3], v3, 0, s[2:3]
	v_addc_co_u32_e64 v68, s[4:5], v68, 0, s[4:5]
	v_addc_co_u32_e64 v69, s[6:7], v69, 0, s[6:7]
	v_cmp_lt_u32_e64 s[0:1], v4, v239
	v_cmp_lt_u32_e64 s[2:3], v10, v239
	v_cmp_lt_u32_e64 s[4:5], v5, v239
	v_cmp_lt_u32_e64 s[6:7], v12, v239
	v_addc_co_u32_e64 v2, s[0:1], v2, 0, s[0:1]
	v_addc_co_u32_e64 v3, s[2:3], v3, 0, s[2:3]
	v_addc_co_u32_e64 v68, s[4:5], v68, 0, s[4:5]
	v_addc_co_u32_e64 v69, s[6:7], v69, 0, s[6:7]
	v_cmp_lt_u32_e64 s[0:1], v7, v239
	v_cmp_lt_u32_e64 s[2:3], v14, v239
	v_cmp_lt_u32_e64 s[4:5], v9, v239
	v_cmp_lt_u32_e64 s[6:7], v15, v239
	v_addc_co_u32_e64 v2, s[0:1], v2, 0, s[0:1]
	v_addc_co_u32_e64 v3, s[2:3], v3, 0, s[2:3]
	v_addc_co_u32_e64 v68, s[4:5], v68, 0, s[4:5]
	v_addc_co_u32_e64 v69, s[6:7], v69, 0, s[6:7]
	v_cmp_lt_u32_e64 s[0:1], v11, v239
	v_cmp_lt_u32_e64 s[2:3], v17, v239
	v_cmp_lt_u32_e64 s[4:5], v13, v239
	v_cmp_lt_u32_e64 s[6:7], v18, v239
	v_addc_co_u32_e64 v2, s[0:1], v2, 0, s[0:1]
	v_addc_co_u32_e64 v3, s[2:3], v3, 0, s[2:3]
	v_addc_co_u32_e64 v68, s[4:5], v68, 0, s[4:5]
	v_addc_co_u32_e64 v69, s[6:7], v69, 0, s[6:7]
	s_cmp_lt_u32 s99, 16
	s_cbranch_scc1 .Ltk_red_sign
; __device__ __forceinline__ void b1_phase(const bf16* QI, const bf16* KI, const float* WI, float* SCRb  , unsigned long long* MASK,
;                                          LAS unsigned char* lds, int vcu, int G, int tid) {
;     ...
;                     unsigned l0 = 0u, l1 = 0u, l2 = 0u, l3 = 0u; const unsigned csign = 0x80000000u;
; #pragma unroll
;                     for (int j = 0; j < 64; j += 4) cnt_lt4(l0, l1, l2, l3, uu[j], uu[j + 1], uu[j + 2], uu[j + 3], csign);
;                     const unsigned less = (l0 + l1) + (l2 + l3);
	v_cmp_lt_u32_e64 s[0:1], v16, v239
	v_cmp_lt_u32_e64 s[2:3], v20, v239
	v_cmp_lt_u32_e64 s[4:5], v19, v239
	v_cmp_lt_u32_e64 s[6:7], v22, v239
	v_addc_co_u32_e64 v2, s[0:1], v2, 0, s[0:1]
	v_addc_co_u32_e64 v3, s[2:3], v3, 0, s[2:3]
	v_addc_co_u32_e64 v68, s[4:5], v68, 0, s[4:5]
	v_addc_co_u32_e64 v69, s[6:7], v69, 0, s[6:7]
	v_cmp_lt_u32_e64 s[0:1], v21, v239
	v_cmp_lt_u32_e64 s[2:3], v24, v239
	v_cmp_lt_u32_e64 s[4:5], v23, v239
	v_cmp_lt_u32_e64 s[6:7], v26, v239
	v_addc_co_u32_e64 v2, s[0:1], v2, 0, s[0:1]
	v_addc_co_u32_e64 v3, s[2:3], v3, 0, s[2:3]
	v_addc_co_u32_e64 v68, s[4:5], v68, 0, s[4:5]
	v_addc_co_u32_e64 v69, s[6:7], v69, 0, s[6:7]
	v_cmp_lt_u32_e64 s[0:1], v25, v239
	v_cmp_lt_u32_e64 s[2:3], v28, v239
	v_cmp_lt_u32_e64 s[4:5], v27, v239
	v_cmp_lt_u32_e64 s[6:7], v30, v239
	v_addc_co_u32_e64 v2, s[0:1], v2, 0, s[0:1]
	v_addc_co_u32_e64 v3, s[2:3], v3, 0, s[2:3]
	v_addc_co_u32_e64 v68, s[4:5], v68, 0, s[4:5]
	v_addc_co_u32_e64 v69, s[6:7], v69, 0, s[6:7]
	v_cmp_lt_u32_e64 s[0:1], v29, v239
	v_cmp_lt_u32_e64 s[2:3], v32, v239
	v_cmp_lt_u32_e64 s[4:5], v31, v239
	v_cmp_lt_u32_e64 s[6:7], v34, v239
	v_addc_co_u32_e64 v2, s[0:1], v2, 0, s[0:1]
	v_addc_co_u32_e64 v3, s[2:3], v3, 0, s[2:3]
	v_addc_co_u32_e64 v68, s[4:5], v68, 0, s[4:5]
	v_addc_co_u32_e64 v69, s[6:7], v69, 0, s[6:7]
	s_cmp_lt_u32 s99, 32
	s_cbranch_scc1 .Ltk_red_sign
	v_cmp_lt_u32_e64 s[0:1], v33, v239
	v_cmp_lt_u32_e64 s[2:3], v37, v239
	v_cmp_lt_u32_e64 s[4:5], v35, v239
	v_cmp_lt_u32_e64 s[6:7], v39, v239
	v_addc_co_u32_e64 v2, s[0:1], v2, 0, s[0:1]
	v_addc_co_u32_e64 v3, s[2:3], v3, 0, s[2:3]
	v_addc_co_u32_e64 v68, s[4:5], v68, 0, s[4:5]
	v_addc_co_u32_e64 v69, s[6:7], v69, 0, s[6:7]
	v_cmp_lt_u32_e64 s[0:1], v36, v239
	v_cmp_lt_u32_e64 s[2:3], v41, v239
	v_cmp_lt_u32_e64 s[4:5], v38, v239
	v_cmp_lt_u32_e64 s[6:7], v43, v239
	v_addc_co_u32_e64 v2, s[0:1], v2, 0, s[0:1]
	v_addc_co_u32_e64 v3, s[2:3], v3, 0, s[2:3]
	v_addc_co_u32_e64 v68, s[4:5], v68, 0, s[4:5]
	v_addc_co_u32_e64 v69, s[6:7], v69, 0, s[6:7]
	v_cmp_lt_u32_e64 s[0:1], v40, v239
	v_cmp_lt_u32_e64 s[2:3], v45, v239
	v_cmp_lt_u32_e64 s[4:5], v42, v239
	v_cmp_lt_u32_e64 s[6:7], v47, v239
	v_addc_co_u32_e64 v2, s[0:1], v2, 0, s[0:1]
	v_addc_co_u32_e64 v3, s[2:3], v3, 0, s[2:3]
	v_addc_co_u32_e64 v68, s[4:5], v68, 0, s[4:5]
	v_addc_co_u32_e64 v69, s[6:7], v69, 0, s[6:7]
	v_cmp_lt_u32_e64 s[0:1], v44, v239
	v_cmp_lt_u32_e64 s[2:3], v49, v239
	v_cmp_lt_u32_e64 s[4:5], v46, v239
	v_cmp_lt_u32_e64 s[6:7], v51, v239
	v_addc_co_u32_e64 v2, s[0:1], v2, 0, s[0:1]
	v_addc_co_u32_e64 v3, s[2:3], v3, 0, s[2:3]
	v_addc_co_u32_e64 v68, s[4:5], v68, 0, s[4:5]
	v_addc_co_u32_e64 v69, s[6:7], v69, 0, s[6:7]
	s_cmp_lt_u32 s99, 48
	s_cbranch_scc1 .Ltk_red_sign
	v_cmp_lt_u32_e64 s[0:1], v48, v239
	v_cmp_lt_u32_e64 s[2:3], v53, v239
	v_cmp_lt_u32_e64 s[4:5], v50, v239
	v_cmp_lt_u32_e64 s[6:7], v55, v239
	v_addc_co_u32_e64 v2, s[0:1], v2, 0, s[0:1]
	v_addc_co_u32_e64 v3, s[2:3], v3, 0, s[2:3]
	v_addc_co_u32_e64 v68, s[4:5], v68, 0, s[4:5]
	v_addc_co_u32_e64 v69, s[6:7], v69, 0, s[6:7]
	v_cmp_lt_u32_e64 s[0:1], v52, v239
	v_cmp_lt_u32_e64 s[2:3], v57, v239
	v_cmp_lt_u32_e64 s[4:5], v54, v239
	v_cmp_lt_u32_e64 s[6:7], v59, v239
	v_addc_co_u32_e64 v2, s[0:1], v2, 0, s[0:1]
	v_addc_co_u32_e64 v3, s[2:3], v3, 0, s[2:3]
	v_addc_co_u32_e64 v68, s[4:5], v68, 0, s[4:5]
	v_addc_co_u32_e64 v69, s[6:7], v69, 0, s[6:7]
	v_cmp_lt_u32_e64 s[0:1], v56, v239
	v_cmp_lt_u32_e64 s[2:3], v61, v239
	v_cmp_lt_u32_e64 s[4:5], v58, v239
	v_cmp_lt_u32_e64 s[6:7], v63, v239
	v_addc_co_u32_e64 v2, s[0:1], v2, 0, s[0:1]
	v_addc_co_u32_e64 v3, s[2:3], v3, 0, s[2:3]
	v_addc_co_u32_e64 v68, s[4:5], v68, 0, s[4:5]
	v_addc_co_u32_e64 v69, s[6:7], v69, 0, s[6:7]
	v_cmp_lt_u32_e64 s[0:1], v60, v239
	v_cmp_lt_u32_e64 s[2:3], v64, v239
	v_cmp_lt_u32_e64 s[4:5], v62, v239
	v_cmp_lt_u32_e64 s[6:7], v65, v239
	v_addc_co_u32_e64 v2, s[0:1], v2, 0, s[0:1]
	v_addc_co_u32_e64 v3, s[2:3], v3, 0, s[2:3]
	v_addc_co_u32_e64 v68, s[4:5], v68, 0, s[4:5]
	v_addc_co_u32_e64 v69, s[6:7], v69, 0, s[6:7]

; __device__ __forceinline__ void b1_phase(const bf16* QI, const bf16* KI, const float* WI, float* SCRb  , unsigned long long* MASK,
;                                          LAS unsigned char* lds, int vcu, int G, int tid) {
;     ...
;                     unsigned l0 = 0u, l1 = 0u, l2 = 0u, l3 = 0u;
; #pragma unroll
;                     for (int j = 0; j < 64; j += 4) cnt_lt4(l0, l1, l2, l3, uu[j], uu[j + 1], uu[j + 2], uu[j + 3], c);
;                     const unsigned less = (l0 + l1) + (l2 + l3);
;                     const int cnt = 4096 - (int)wave_sum_u32(less);
.LBB0_676:
	s_lshr_b32 s98, s99, 4
	s_lshl_b32 s98, s98, 4
	s_sub_u32 s98, 48, s98
	v_mov_b32_e32 v70, s98
	v_mov_b32_e32 v71, 0
	v_mov_b32_e32 v72, 0
	v_mov_b32_e32 v73, 0
	v_cmp_lt_u32_e64 s[2:3], v67, v69
	v_cmp_lt_u32_e64 s[4:5], v6, v69
	v_cmp_lt_u32_e64 s[8:9], v0, v69
	v_cmp_lt_u32_e64 s[10:11], v8, v69
	v_addc_co_u32_e64 v70, s[2:3], v70, 0, s[2:3]
	v_addc_co_u32_e64 v71, s[4:5], v71, 0, s[4:5]
	v_addc_co_u32_e64 v72, s[8:9], v72, 0, s[8:9]
	v_addc_co_u32_e64 v73, s[10:11], v73, 0, s[10:11]
	v_cmp_lt_u32_e64 s[2:3], v4, v69
	v_cmp_lt_u32_e64 s[4:5], v10, v69
	v_cmp_lt_u32_e64 s[8:9], v5, v69
	v_cmp_lt_u32_e64 s[10:11], v12, v69
	v_addc_co_u32_e64 v70, s[2:3], v70, 0, s[2:3]
	v_addc_co_u32_e64 v71, s[4:5], v71, 0, s[4:5]
	v_addc_co_u32_e64 v72, s[8:9], v72, 0, s[8:9]
	v_addc_co_u32_e64 v73, s[10:11], v73, 0, s[10:11]
	v_cmp_lt_u32_e64 s[2:3], v7, v69
	v_cmp_lt_u32_e64 s[4:5], v14, v69
	v_cmp_lt_u32_e64 s[8:9], v9, v69
	v_cmp_lt_u32_e64 s[10:11], v15, v69
	v_addc_co_u32_e64 v70, s[2:3], v70, 0, s[2:3]
	v_addc_co_u32_e64 v71, s[4:5], v71, 0, s[4:5]
	v_addc_co_u32_e64 v72, s[8:9], v72, 0, s[8:9]
	v_addc_co_u32_e64 v73, s[10:11], v73, 0, s[10:11]
	v_cmp_lt_u32_e64 s[2:3], v11, v69
	v_cmp_lt_u32_e64 s[4:5], v17, v69
	v_cmp_lt_u32_e64 s[8:9], v13, v69
	v_cmp_lt_u32_e64 s[10:11], v18, v69
	v_addc_co_u32_e64 v70, s[2:3], v70, 0, s[2:3]
	v_addc_co_u32_e64 v71, s[4:5], v71, 0, s[4:5]
	v_addc_co_u32_e64 v72, s[8:9], v72, 0, s[8:9]
	v_addc_co_u32_e64 v73, s[10:11], v73, 0, s[10:11]
	s_cmp_lt_u32 s99, 16
	s_cbranch_scc1 .Ltk_red_loop
	v_cmp_lt_u32_e64 s[2:3], v16, v69
	v_cmp_lt_u32_e64 s[4:5], v20, v69
	v_cmp_lt_u32_e64 s[8:9], v19, v69
	v_cmp_lt_u32_e64 s[10:11], v22, v69
	v_addc_co_u32_e64 v70, s[2:3], v70, 0, s[2:3]
	v_addc_co_u32_e64 v71, s[4:5], v71, 0, s[4:5]
	v_addc_co_u32_e64 v72, s[8:9], v72, 0, s[8:9]
	v_addc_co_u32_e64 v73, s[10:11], v73, 0, s[10:11]
	v_cmp_lt_u32_e64 s[2:3], v21, v69
	v_cmp_lt_u32_e64 s[4:5], v24, v69
	v_cmp_lt_u32_e64 s[8:9], v23, v69
	v_cmp_lt_u32_e64 s[10:11], v26, v69
	v_addc_co_u32_e64 v70, s[2:3], v70, 0, s[2:3]
	v_addc_co_u32_e64 v71, s[4:5], v71, 0, s[4:5]
	v_addc_co_u32_e64 v72, s[8:9], v72, 0, s[8:9]
	v_addc_co_u32_e64 v73, s[10:11], v73, 0, s[10:11]
	v_cmp_lt_u32_e64 s[2:3], v25, v69
	v_cmp_lt_u32_e64 s[4:5], v28, v69
	v_cmp_lt_u32_e64 s[8:9], v27, v69
	v_cmp_lt_u32_e64 s[10:11], v30, v69
	v_addc_co_u32_e64 v70, s[2:3], v70, 0, s[2:3]
	v_addc_co_u32_e64 v71, s[4:5], v71, 0, s[4:5]
	v_addc_co_u32_e64 v72, s[8:9], v72, 0, s[8:9]
	v_addc_co_u32_e64 v73, s[10:11], v73, 0, s[10:11]
	v_cmp_lt_u32_e64 s[2:3], v29, v69
	v_cmp_lt_u32_e64 s[4:5], v32, v69
	v_cmp_lt_u32_e64 s[8:9], v31, v69
	v_cmp_lt_u32_e64 s[10:11], v34, v69
	v_addc_co_u32_e64 v70, s[2:3], v70, 0, s[2:3]
	v_addc_co_u32_e64 v71, s[4:5], v71, 0, s[4:5]
	v_addc_co_u32_e64 v72, s[8:9], v72, 0, s[8:9]
	v_addc_co_u32_e64 v73, s[10:11], v73, 0, s[10:11]
	s_cmp_lt_u32 s99, 32
	s_cbranch_scc1 .Ltk_red_loop
	v_cmp_lt_u32_e64 s[2:3], v33, v69
	v_cmp_lt_u32_e64 s[4:5], v37, v69
	v_cmp_lt_u32_e64 s[8:9], v35, v69
	v_cmp_lt_u32_e64 s[10:11], v39, v69
	v_addc_co_u32_e64 v70, s[2:3], v70, 0, s[2:3]
	v_addc_co_u32_e64 v71, s[4:5], v71, 0, s[4:5]
	v_addc_co_u32_e64 v72, s[8:9], v72, 0, s[8:9]
	v_addc_co_u32_e64 v73, s[10:11], v73, 0, s[10:11]
	v_cmp_lt_u32_e64 s[2:3], v36, v69
	v_cmp_lt_u32_e64 s[4:5], v41, v69
	v_cmp_lt_u32_e64 s[8:9], v38, v69
	v_cmp_lt_u32_e64 s[10:11], v43, v69
	v_addc_co_u32_e64 v70, s[2:3], v70, 0, s[2:3]
	v_addc_co_u32_e64 v71, s[4:5], v71, 0, s[4:5]
	v_addc_co_u32_e64 v72, s[8:9], v72, 0, s[8:9]
	v_addc_co_u32_e64 v73, s[10:11], v73, 0, s[10:11]
	v_cmp_lt_u32_e64 s[2:3], v40, v69
	v_cmp_lt_u32_e64 s[4:5], v45, v69
	v_cmp_lt_u32_e64 s[8:9], v42, v69
	v_cmp_lt_u32_e64 s[10:11], v47, v69
	v_addc_co_u32_e64 v70, s[2:3], v70, 0, s[2:3]
	v_addc_co_u32_e64 v71, s[4:5], v71, 0, s[4:5]
	v_addc_co_u32_e64 v72, s[8:9], v72, 0, s[8:9]
	v_addc_co_u32_e64 v73, s[10:11], v73, 0, s[10:11]
	v_cmp_lt_u32_e64 s[2:3], v44, v69
	v_cmp_lt_u32_e64 s[4:5], v49, v69
	v_cmp_lt_u32_e64 s[8:9], v46, v69
	v_cmp_lt_u32_e64 s[10:11], v51, v69
	v_addc_co_u32_e64 v70, s[2:3], v70, 0, s[2:3]
	v_addc_co_u32_e64 v71, s[4:5], v71, 0, s[4:5]
	v_addc_co_u32_e64 v72, s[8:9], v72, 0, s[8:9]
	v_addc_co_u32_e64 v73, s[10:11], v73, 0, s[10:11]
	s_cmp_lt_u32 s99, 48
	s_cbranch_scc1 .Ltk_red_loop
	v_cmp_lt_u32_e64 s[2:3], v48, v69
	v_cmp_lt_u32_e64 s[4:5], v53, v69
	v_cmp_lt_u32_e64 s[8:9], v50, v69
	v_cmp_lt_u32_e64 s[10:11], v55, v69
	v_addc_co_u32_e64 v70, s[2:3], v70, 0, s[2:3]
	v_addc_co_u32_e64 v71, s[4:5], v71, 0, s[4:5]
	v_addc_co_u32_e64 v72, s[8:9], v72, 0, s[8:9]
	v_addc_co_u32_e64 v73, s[10:11], v73, 0, s[10:11]
	v_cmp_lt_u32_e64 s[2:3], v52, v69
	v_cmp_lt_u32_e64 s[4:5], v57, v69
	v_cmp_lt_u32_e64 s[8:9], v54, v69
	v_cmp_lt_u32_e64 s[10:11], v59, v69
	v_addc_co_u32_e64 v70, s[2:3], v70, 0, s[2:3]
	v_addc_co_u32_e64 v71, s[4:5], v71, 0, s[4:5]
	v_addc_co_u32_e64 v72, s[8:9], v72, 0, s[8:9]
	v_addc_co_u32_e64 v73, s[10:11], v73, 0, s[10:11]
	v_cmp_lt_u32_e64 s[2:3], v56, v69
	v_cmp_lt_u32_e64 s[4:5], v61, v69
	v_cmp_lt_u32_e64 s[8:9], v58, v69
	v_cmp_lt_u32_e64 s[10:11], v63, v69
	v_addc_co_u32_e64 v70, s[2:3], v70, 0, s[2:3]
	v_addc_co_u32_e64 v71, s[4:5], v71, 0, s[4:5]
	v_addc_co_u32_e64 v72, s[8:9], v72, 0, s[8:9]
	v_addc_co_u32_e64 v73, s[10:11], v73, 0, s[10:11]
	v_cmp_lt_u32_e64 s[2:3], v60, v69
	v_cmp_lt_u32_e64 s[4:5], v64, v69
	v_cmp_lt_u32_e64 s[8:9], v62, v69
	v_cmp_lt_u32_e64 s[10:11], v65, v69
	v_addc_co_u32_e64 v70, s[2:3], v70, 0, s[2:3]
	v_addc_co_u32_e64 v71, s[4:5], v71, 0, s[4:5]
	v_addc_co_u32_e64 v72, s[8:9], v72, 0, s[8:9]
	v_addc_co_u32_e64 v73, s[10:11], v73, 0, s[10:11]
